# v28 + nt on GEMM3 epilogue residual (x) loads, their last use
# speedup vs baseline: 1.0134x; 1.0134x over previous
.LBB0_507:
	ds_read_b128 v[128:131], v229
	ds_read_b128 v[132:135], v229 offset:1024
	ds_read_b128 v[136:139], v229 offset:2048
	ds_read_b128 v[140:143], v229 offset:3072
	ds_read_b128 v[144:147], v230
	ds_read_b128 v[148:151], v230 offset:1024
	ds_read_b128 v[152:155], v230 offset:2048
	ds_read_b128 v[156:159], v230 offset:3072
	s_add_u32 s44, s42, 0x10000
	s_addc_u32 s45, s43, 0
	s_cmp_eq_u32 s83, 12
	s_cselect_b32 s50, s21, s44
	s_cselect_b32 s51, s8, s45
	s_cselect_b32 s48, s29, s80
	s_cselect_b32 s49, s27, s81
	s_add_u32 s46, s50, 0x8000
	s_addc_u32 s47, s51, 0
	v_lshl_add_u64 v[208:209], s[42:43], 0, v[200:201]
	s_add_i32 m0, s23, 0xc000
	ds_read_b128 v[160:163], v231
	ds_read_b128 v[164:167], v231 offset:1024
	ds_read_b128 v[168:171], v231 offset:2048
	ds_read_b128 v[172:175], v231 offset:3072
	ds_read_b128 v[176:179], v231 offset:4096
	ds_read_b128 v[180:183], v231 offset:5120
	ds_read_b128 v[184:187], v231 offset:6144
	ds_read_b128 v[188:191], v231 offset:7168
	global_load_lds_dwordx4 v[208:209], off
	v_lshl_add_u64 v[208:209], s[42:43], 0, v[202:203]
	s_add_i32 m0, s23, 0xe000
	s_nop 0
	global_load_lds_dwordx4 v[208:209], off
	s_waitcnt vmcnt(8)
	s_waitcnt lgkmcnt(0)
	s_barrier
	s_setprio 1
	s_waitcnt lgkmcnt(0)
	v_mfma_f32_16x16x32_bf16 v[124:127], v[128:131], v[160:163], v[124:127]
	v_mfma_f32_16x16x32_bf16 v[120:123], v[136:139], v[160:163], v[120:123]
	v_mfma_f32_16x16x32_bf16 v[108:111], v[128:131], v[168:171], v[108:111]
	v_mfma_f32_16x16x32_bf16 v[104:107], v[136:139], v[168:171], v[104:107]
	v_mfma_f32_16x16x32_bf16 v[92:95], v[128:131], v[176:179], v[92:95]
	v_mfma_f32_16x16x32_bf16 v[88:91], v[136:139], v[176:179], v[88:91]
	v_mfma_f32_16x16x32_bf16 v[76:79], v[128:131], v[184:187], v[76:79]
	v_mfma_f32_16x16x32_bf16 v[72:75], v[136:139], v[184:187], v[72:75]
	v_mfma_f32_16x16x32_bf16 v[124:127], v[132:135], v[164:167], v[124:127]
	v_mfma_f32_16x16x32_bf16 v[120:123], v[140:143], v[164:167], v[120:123]
	v_mfma_f32_16x16x32_bf16 v[108:111], v[132:135], v[172:175], v[108:111]
	v_mfma_f32_16x16x32_bf16 v[104:107], v[140:143], v[172:175], v[104:107]
	v_mfma_f32_16x16x32_bf16 v[92:95], v[132:135], v[180:183], v[92:95]
	v_mfma_f32_16x16x32_bf16 v[88:91], v[140:143], v[180:183], v[88:91]
	v_mfma_f32_16x16x32_bf16 v[76:79], v[132:135], v[188:191], v[76:79]
	v_mfma_f32_16x16x32_bf16 v[72:75], v[140:143], v[188:191], v[72:75]
	s_setprio 0
	s_setprio 1
	v_mfma_f32_16x16x32_bf16 v[116:119], v[144:147], v[160:163], v[116:119]
	v_mfma_f32_16x16x32_bf16 v[112:115], v[152:155], v[160:163], v[112:115]
	v_mfma_f32_16x16x32_bf16 v[100:103], v[144:147], v[168:171], v[100:103]
	v_mfma_f32_16x16x32_bf16 v[96:99], v[152:155], v[168:171], v[96:99]
	v_mfma_f32_16x16x32_bf16 v[84:87], v[144:147], v[176:179], v[84:87]
	v_mfma_f32_16x16x32_bf16 v[80:83], v[152:155], v[176:179], v[80:83]
	v_mfma_f32_16x16x32_bf16 v[68:71], v[144:147], v[184:187], v[68:71]
	v_mfma_f32_16x16x32_bf16 v[64:67], v[152:155], v[184:187], v[64:67]
	v_mfma_f32_16x16x32_bf16 v[116:119], v[148:151], v[164:167], v[116:119]
	v_mfma_f32_16x16x32_bf16 v[112:115], v[156:159], v[164:167], v[112:115]
	v_mfma_f32_16x16x32_bf16 v[100:103], v[148:151], v[172:175], v[100:103]
	v_mfma_f32_16x16x32_bf16 v[96:99], v[156:159], v[172:175], v[96:99]
	v_mfma_f32_16x16x32_bf16 v[84:87], v[148:151], v[180:183], v[84:87]
	v_mfma_f32_16x16x32_bf16 v[80:83], v[156:159], v[180:183], v[80:83]
	v_mfma_f32_16x16x32_bf16 v[68:71], v[148:151], v[188:191], v[68:71]
	v_mfma_f32_16x16x32_bf16 v[64:67], v[156:159], v[188:191], v[64:67]
	s_setprio 0
	s_barrier
	s_add_i32 s42, s77, s35
	v_lshl_add_u64 v[208:209], s[48:49], 0, v[194:195]
	s_mov_b32 m0, s42
	ds_read_b128 v[160:163], v231 offset:16384
	ds_read_b128 v[164:167], v231 offset:17408
	ds_read_b128 v[168:171], v231 offset:18432
	ds_read_b128 v[172:175], v231 offset:19456
	ds_read_b128 v[176:179], v231 offset:20480
	ds_read_b128 v[180:183], v231 offset:21504
	ds_read_b128 v[184:187], v231 offset:22528
	ds_read_b128 v[188:191], v231 offset:23552
	global_load_lds_dwordx4 v[208:209], off
	s_add_i32 m0, s42, 0x2000
	s_add_u32 s42, s48, 0x40000
	v_lshl_add_u64 v[210:211], s[48:49], 0, v[198:199]
	s_addc_u32 s43, s49, 0
	s_add_i32 s84, s78, s35
	global_load_lds_dwordx4 v[210:211], off
	v_lshl_add_u64 v[212:213], s[42:43], 0, v[194:195]
	s_mov_b32 m0, s84
	s_nop 0
	global_load_lds_dwordx4 v[212:213], off
	v_lshl_add_u64 v[212:213], s[42:43], 0, v[198:199]
	s_add_i32 m0, s84, 0x2000
	s_nop 0
	global_load_lds_dwordx4 v[212:213], off
	v_lshl_add_u64 v[212:213], s[50:51], 0, v[192:193]
	s_mov_b32 m0, s23
	s_nop 0
	global_load_lds_dwordx4 v[212:213], off
	v_lshl_add_u64 v[212:213], s[50:51], 0, v[196:197]
	s_mov_b32 m0, s56
	s_nop 0
	global_load_lds_dwordx4 v[212:213], off
	s_waitcnt vmcnt(8)
	s_waitcnt lgkmcnt(0)
	s_barrier
	s_setprio 1
	s_waitcnt lgkmcnt(0)
	v_mfma_f32_16x16x32_bf16 v[60:63], v[128:131], v[160:163], v[60:63]
	v_mfma_f32_16x16x32_bf16 v[56:59], v[136:139], v[160:163], v[56:59]
	v_mfma_f32_16x16x32_bf16 v[44:47], v[128:131], v[168:171], v[44:47]
	v_mfma_f32_16x16x32_bf16 v[40:43], v[136:139], v[168:171], v[40:43]
	v_mfma_f32_16x16x32_bf16 v[28:31], v[128:131], v[176:179], v[28:31]
	v_mfma_f32_16x16x32_bf16 v[24:27], v[136:139], v[176:179], v[24:27]
	v_mfma_f32_16x16x32_bf16 v[12:15], v[128:131], v[184:187], v[12:15]
	v_mfma_f32_16x16x32_bf16 v[8:11], v[136:139], v[184:187], v[8:11]
	v_mfma_f32_16x16x32_bf16 v[60:63], v[132:135], v[164:167], v[60:63]
	v_mfma_f32_16x16x32_bf16 v[56:59], v[140:143], v[164:167], v[56:59]
	v_mfma_f32_16x16x32_bf16 v[44:47], v[132:135], v[172:175], v[44:47]
	v_mfma_f32_16x16x32_bf16 v[40:43], v[140:143], v[172:175], v[40:43]
	v_mfma_f32_16x16x32_bf16 v[28:31], v[132:135], v[180:183], v[28:31]
	v_mfma_f32_16x16x32_bf16 v[24:27], v[140:143], v[180:183], v[24:27]
	v_mfma_f32_16x16x32_bf16 v[12:15], v[132:135], v[188:191], v[12:15]
	v_mfma_f32_16x16x32_bf16 v[8:11], v[140:143], v[188:191], v[8:11]
	s_setprio 0
	s_setprio 1
	v_mfma_f32_16x16x32_bf16 v[52:55], v[144:147], v[160:163], v[52:55]
	v_mfma_f32_16x16x32_bf16 v[48:51], v[152:155], v[160:163], v[48:51]
	v_mfma_f32_16x16x32_bf16 v[36:39], v[144:147], v[168:171], v[36:39]
	v_mfma_f32_16x16x32_bf16 v[32:35], v[152:155], v[168:171], v[32:35]
	v_mfma_f32_16x16x32_bf16 v[20:23], v[144:147], v[176:179], v[20:23]
	v_mfma_f32_16x16x32_bf16 v[16:19], v[152:155], v[176:179], v[16:19]
	v_mfma_f32_16x16x32_bf16 v[4:7], v[144:147], v[184:187], v[4:7]
	v_mfma_f32_16x16x32_bf16 v[0:3], v[152:155], v[184:187], v[0:3]
	v_mfma_f32_16x16x32_bf16 v[52:55], v[148:151], v[164:167], v[52:55]
	v_mfma_f32_16x16x32_bf16 v[48:51], v[156:159], v[164:167], v[48:51]
	v_mfma_f32_16x16x32_bf16 v[36:39], v[148:151], v[172:175], v[36:39]
	v_mfma_f32_16x16x32_bf16 v[32:35], v[156:159], v[172:175], v[32:35]
	v_mfma_f32_16x16x32_bf16 v[20:23], v[148:151], v[180:183], v[20:23]
	v_mfma_f32_16x16x32_bf16 v[16:19], v[156:159], v[180:183], v[16:19]
	v_mfma_f32_16x16x32_bf16 v[4:7], v[148:151], v[188:191], v[4:7]
	v_mfma_f32_16x16x32_bf16 v[0:3], v[156:159], v[188:191], v[0:3]
	s_setprio 0
	s_barrier
	s_add_i32 s84, 0, 0x18000
	s_add_i32 s85, 0, 0x1c000
	v_add_u32_e32 v140, s84, v228
	v_add_u32_e32 v156, s85, v228
	ds_read_b128 v[128:131], v140
	ds_read_b128 v[132:135], v140 offset:1024
	ds_read_b128 v[136:139], v140 offset:2048
	ds_read_b128 v[140:143], v140 offset:3072
	ds_read_b128 v[144:147], v156
	ds_read_b128 v[148:151], v156 offset:1024
	ds_read_b128 v[152:155], v156 offset:2048
	ds_read_b128 v[156:159], v156 offset:3072
	s_add_u32 s42, s50, 0x2000
	s_addc_u32 s43, s51, 0
	s_mov_b32 m0, s57
	v_lshl_add_u64 v[212:213], s[42:43], 0, v[192:193]
	ds_read_b128 v[160:163], v231 offset:32768
	ds_read_b128 v[164:167], v231 offset:33792
	ds_read_b128 v[168:171], v231 offset:34816
	ds_read_b128 v[172:175], v231 offset:35840
	ds_read_b128 v[176:179], v231 offset:36864
	ds_read_b128 v[180:183], v231 offset:37888
	ds_read_b128 v[184:187], v231 offset:38912
	ds_read_b128 v[188:191], v231 offset:39936
	global_load_lds_dwordx4 v[212:213], off
	v_lshl_add_u64 v[212:213], s[42:43], 0, v[196:197]
	s_mov_b32 m0, s59
	s_nop 0
	global_load_lds_dwordx4 v[212:213], off
	s_waitcnt vmcnt(8)
	s_waitcnt lgkmcnt(0)
	s_barrier
	s_setprio 1
	s_waitcnt lgkmcnt(0)
	v_mfma_f32_16x16x32_bf16 v[124:127], v[128:131], v[160:163], v[124:127]
	v_mfma_f32_16x16x32_bf16 v[120:123], v[136:139], v[160:163], v[120:123]
	v_mfma_f32_16x16x32_bf16 v[108:111], v[128:131], v[168:171], v[108:111]
	v_mfma_f32_16x16x32_bf16 v[104:107], v[136:139], v[168:171], v[104:107]
	v_mfma_f32_16x16x32_bf16 v[92:95], v[128:131], v[176:179], v[92:95]
	v_mfma_f32_16x16x32_bf16 v[88:91], v[136:139], v[176:179], v[88:91]
	v_mfma_f32_16x16x32_bf16 v[76:79], v[128:131], v[184:187], v[76:79]
	v_mfma_f32_16x16x32_bf16 v[72:75], v[136:139], v[184:187], v[72:75]
	v_mfma_f32_16x16x32_bf16 v[124:127], v[132:135], v[164:167], v[124:127]
	v_mfma_f32_16x16x32_bf16 v[120:123], v[140:143], v[164:167], v[120:123]
	v_mfma_f32_16x16x32_bf16 v[108:111], v[132:135], v[172:175], v[108:111]
	v_mfma_f32_16x16x32_bf16 v[104:107], v[140:143], v[172:175], v[104:107]
	v_mfma_f32_16x16x32_bf16 v[92:95], v[132:135], v[180:183], v[92:95]
	v_mfma_f32_16x16x32_bf16 v[88:91], v[140:143], v[180:183], v[88:91]
	v_mfma_f32_16x16x32_bf16 v[76:79], v[132:135], v[188:191], v[76:79]
	v_mfma_f32_16x16x32_bf16 v[72:75], v[140:143], v[188:191], v[72:75]
	s_setprio 0
	s_setprio 1
	v_mfma_f32_16x16x32_bf16 v[116:119], v[144:147], v[160:163], v[116:119]
	v_mfma_f32_16x16x32_bf16 v[112:115], v[152:155], v[160:163], v[112:115]
	v_mfma_f32_16x16x32_bf16 v[100:103], v[144:147], v[168:171], v[100:103]
	v_mfma_f32_16x16x32_bf16 v[96:99], v[152:155], v[168:171], v[96:99]
	v_mfma_f32_16x16x32_bf16 v[84:87], v[144:147], v[176:179], v[84:87]
	v_mfma_f32_16x16x32_bf16 v[80:83], v[152:155], v[176:179], v[80:83]
	v_mfma_f32_16x16x32_bf16 v[68:71], v[144:147], v[184:187], v[68:71]
	v_mfma_f32_16x16x32_bf16 v[64:67], v[152:155], v[184:187], v[64:67]
	v_mfma_f32_16x16x32_bf16 v[116:119], v[148:151], v[164:167], v[116:119]
	v_mfma_f32_16x16x32_bf16 v[112:115], v[156:159], v[164:167], v[112:115]
	v_mfma_f32_16x16x32_bf16 v[100:103], v[148:151], v[172:175], v[100:103]
	v_mfma_f32_16x16x32_bf16 v[96:99], v[156:159], v[172:175], v[96:99]
	v_mfma_f32_16x16x32_bf16 v[84:87], v[148:151], v[180:183], v[84:87]
	v_mfma_f32_16x16x32_bf16 v[80:83], v[156:159], v[180:183], v[80:83]
	v_mfma_f32_16x16x32_bf16 v[68:71], v[148:151], v[188:191], v[68:71]
	v_mfma_f32_16x16x32_bf16 v[64:67], v[156:159], v[188:191], v[64:67]
	s_setprio 0
	s_barrier
	s_add_i32 s42, s84, s35
	v_lshl_add_u64 v[208:209], v[208:209], 0, s[16:17]
	s_mov_b32 m0, s42
	ds_read_b128 v[160:163], v231 offset:49152
	ds_read_b128 v[164:167], v231 offset:50176
	ds_read_b128 v[168:171], v231 offset:51200
	ds_read_b128 v[172:175], v231 offset:52224
	ds_read_b128 v[176:179], v231 offset:53248
	ds_read_b128 v[180:183], v231 offset:54272
	ds_read_b128 v[184:187], v231 offset:55296
	ds_read_b128 v[188:191], v231 offset:56320
	global_load_lds_dwordx4 v[208:209], off
	s_add_i32 m0, s42, 0x2000
	s_add_u32 s42, s48, 0x40080
	v_lshl_add_u64 v[208:209], v[210:211], 0, s[16:17]
	s_addc_u32 s43, s49, 0
	s_add_i32 s48, s85, s35
	global_load_lds_dwordx4 v[208:209], off
	v_lshl_add_u64 v[208:209], s[42:43], 0, v[194:195]
	s_mov_b32 m0, s48
	s_nop 0
	global_load_lds_dwordx4 v[208:209], off
	v_lshl_add_u64 v[208:209], s[42:43], 0, v[198:199]
	s_add_i32 m0, s48, 0x2000
	s_nop 0
	global_load_lds_dwordx4 v[208:209], off
	v_lshl_add_u64 v[208:209], s[46:47], 0, v[192:193]
	s_mov_b32 m0, s75
	s_nop 0
	global_load_lds_dwordx4 v[208:209], off
	v_lshl_add_u64 v[208:209], s[46:47], 0, v[196:197]
	s_mov_b32 m0, s76
	s_nop 0
	global_load_lds_dwordx4 v[208:209], off
	s_waitcnt vmcnt(8)
	s_waitcnt lgkmcnt(0)
	s_barrier
	s_setprio 1
	s_waitcnt lgkmcnt(0)
	v_mfma_f32_16x16x32_bf16 v[60:63], v[128:131], v[160:163], v[60:63]
	v_mfma_f32_16x16x32_bf16 v[56:59], v[136:139], v[160:163], v[56:59]
	v_mfma_f32_16x16x32_bf16 v[44:47], v[128:131], v[168:171], v[44:47]
	v_mfma_f32_16x16x32_bf16 v[40:43], v[136:139], v[168:171], v[40:43]
	v_mfma_f32_16x16x32_bf16 v[28:31], v[128:131], v[176:179], v[28:31]
	v_mfma_f32_16x16x32_bf16 v[24:27], v[136:139], v[176:179], v[24:27]
	v_mfma_f32_16x16x32_bf16 v[12:15], v[128:131], v[184:187], v[12:15]
	v_mfma_f32_16x16x32_bf16 v[8:11], v[136:139], v[184:187], v[8:11]
	v_mfma_f32_16x16x32_bf16 v[60:63], v[132:135], v[164:167], v[60:63]
	v_mfma_f32_16x16x32_bf16 v[56:59], v[140:143], v[164:167], v[56:59]
	v_mfma_f32_16x16x32_bf16 v[44:47], v[132:135], v[172:175], v[44:47]
	v_mfma_f32_16x16x32_bf16 v[40:43], v[140:143], v[172:175], v[40:43]
	v_mfma_f32_16x16x32_bf16 v[28:31], v[132:135], v[180:183], v[28:31]
	v_mfma_f32_16x16x32_bf16 v[24:27], v[140:143], v[180:183], v[24:27]
	v_mfma_f32_16x16x32_bf16 v[12:15], v[132:135], v[188:191], v[12:15]
	v_mfma_f32_16x16x32_bf16 v[8:11], v[140:143], v[188:191], v[8:11]
	s_setprio 0
	s_setprio 1
	v_mfma_f32_16x16x32_bf16 v[52:55], v[144:147], v[160:163], v[52:55]
	v_mfma_f32_16x16x32_bf16 v[48:51], v[152:155], v[160:163], v[48:51]
	v_mfma_f32_16x16x32_bf16 v[36:39], v[144:147], v[168:171], v[36:39]
	v_mfma_f32_16x16x32_bf16 v[32:35], v[152:155], v[168:171], v[32:35]
	v_mfma_f32_16x16x32_bf16 v[20:23], v[144:147], v[176:179], v[20:23]
	v_mfma_f32_16x16x32_bf16 v[16:19], v[152:155], v[176:179], v[16:19]
	v_mfma_f32_16x16x32_bf16 v[4:7], v[144:147], v[184:187], v[4:7]
	v_mfma_f32_16x16x32_bf16 v[0:3], v[152:155], v[184:187], v[0:3]
	v_mfma_f32_16x16x32_bf16 v[52:55], v[148:151], v[164:167], v[52:55]
	v_mfma_f32_16x16x32_bf16 v[48:51], v[156:159], v[164:167], v[48:51]
	v_mfma_f32_16x16x32_bf16 v[36:39], v[148:151], v[172:175], v[36:39]
	v_mfma_f32_16x16x32_bf16 v[32:35], v[156:159], v[172:175], v[32:35]
	v_mfma_f32_16x16x32_bf16 v[20:23], v[148:151], v[180:183], v[20:23]
	v_mfma_f32_16x16x32_bf16 v[16:19], v[156:159], v[180:183], v[16:19]
	v_mfma_f32_16x16x32_bf16 v[4:7], v[148:151], v[188:191], v[4:7]
	v_mfma_f32_16x16x32_bf16 v[0:3], v[156:159], v[188:191], v[0:3]
	s_setprio 0
	s_barrier
	s_add_i32 s83, s83, 2
	s_add_u32 s80, s80, 0x100
	s_addc_u32 s81, s81, 0
	s_cmp_gt_u32 s83, 13
	s_mov_b64 s[42:43], s[44:45]
	s_cbranch_scc0 .LBB0_507
	v_mov_b32_e32 v233, v227
	v_mov_b32_e32 v144, v226
	s_lshl_b32 s8, s22, 8
	s_or_b32 s8, s8, s73
	v_lshlrev_b32_e32 v208, 3, v233
	v_add_u32_e32 v128, s8, v208
	s_lshr_b32 s8, s20, 4
	s_mul_i32 s42, s8, 0x1800
	s_ashr_i32 s43, s42, 31
	s_lshl_b64 s[42:43], s[42:43], 2
	s_add_u32 s42, s69, s42
	v_ashrrev_i32_e32 v129, 31, v128
	v_add_u32_e32 v210, s72, v144
	s_addc_u32 s43, s70, s43
	v_lshlrev_b64 v[212:213], 2, v[128:129]
	v_lshl_add_u32 v216, s20, 8, v210
	v_lshl_add_u64 v[214:215], s[42:43], 0, v[212:213]
	v_ashrrev_i32_e32 v217, 31, v216
	v_add_co_u32_e32 v128, vcc, s65, v214
	v_lshl_add_u64 v[218:219], s[36:37], 0, v[212:213]
	v_lshlrev_b64 v[144:145], 12, v[216:217]
	v_add_u32_e32 v224, 16, v216
	v_lshl_add_u64 v[132:133], v[214:215], 0, s[10:11]
	v_addc_co_u32_e32 v129, vcc, 0, v215, vcc
	v_lshl_add_u64 v[144:145], v[218:219], 0, v[144:145]
	v_ashrrev_i32_e32 v225, 31, v224
	global_load_dwordx4 v[140:143], v[128:129], off nt
	s_nop 0
	global_load_dwordx4 v[128:131], v[132:133], off offset:528 nt
	global_load_dwordx4 v[136:139], v[132:133], off offset:16 nt
	s_nop 0
	global_load_dwordx4 v[132:135], v[132:133], off offset:512 nt
	s_nop 0
	global_load_dwordx4 v[234:237], v[144:145], off offset:16 nt
	global_load_dwordx4 v[238:241], v[144:145], off nt
	global_load_dwordx4 v[242:245], v[144:145], off offset:528 nt
	global_load_dwordx4 v[246:249], v[144:145], off offset:512 nt
	v_lshlrev_b64 v[144:145], 12, v[224:225]
	v_add_u32_e32 v222, 32, v216
	v_lshl_add_u64 v[144:145], v[218:219], 0, v[144:145]
	v_ashrrev_i32_e32 v223, 31, v222
	global_load_dwordx4 v[184:187], v[144:145], off offset:16 nt
	global_load_dwordx4 v[188:191], v[144:145], off nt
	global_load_dwordx4 v[176:179], v[144:145], off offset:528 nt
	global_load_dwordx4 v[180:183], v[144:145], off offset:512 nt
	v_lshlrev_b64 v[144:145], 12, v[222:223]
	v_add_u32_e32 v220, 48, v216
	v_lshl_add_u64 v[144:145], v[218:219], 0, v[144:145]
	v_ashrrev_i32_e32 v221, 31, v220
	global_load_dwordx4 v[168:171], v[144:145], off offset:16 nt
	global_load_dwordx4 v[172:175], v[144:145], off nt
	global_load_dwordx4 v[160:163], v[144:145], off offset:528 nt
	global_load_dwordx4 v[164:167], v[144:145], off offset:512 nt
	v_lshlrev_b64 v[144:145], 12, v[220:221]
	v_lshl_add_u64 v[148:149], v[218:219], 0, v[144:145]
	global_load_dwordx4 v[152:155], v[148:149], off offset:16 nt
	global_load_dwordx4 v[156:159], v[148:149], off nt
	global_load_dwordx4 v[144:147], v[148:149], off offset:528 nt
	s_nop 0
	global_load_dwordx4 v[148:151], v[148:149], off offset:512 nt
	v_and_b32_e32 v211, 64, v232
	v_xor_b32_e32 v209, 16, v232
	v_add_u32_e32 v211, 64, v211
	v_cmp_lt_i32_e32 vcc, v209, v211
	v_xor_b32_e32 v250, 32, v232
	s_lshl_b32 s42, s22, 2
	v_cndmask_b32_e32 v209, v232, v209, vcc
	v_cmp_lt_i32_e32 vcc, v250, v211
	v_lshlrev_b32_e32 v209, 2, v209
	s_ashr_i32 s43, s42, 31
	v_cndmask_b32_e32 v211, v232, v250, vcc
	v_lshlrev_b32_e32 v211, 2, v211
	v_cmp_eq_u32_e32 vcc, 0, v233
	s_waitcnt vmcnt(0)
	v_pk_fma_f32 v[126:127], v[126:127], v[142:143], v[240:241]
	v_pk_fma_f32 v[124:125], v[124:125], v[140:141], v[238:239]
	v_pk_fma_f32 v[120:121], v[120:121], v[136:137], v[234:235]
	v_mul_f32_e32 v233, v125, v125
	v_mul_f32_e32 v234, v127, v127
	v_fmac_f32_e32 v233, v124, v124
	v_fmac_f32_e32 v234, v126, v126
	v_add_f32_e32 v233, v233, v234
	v_mul_f32_e32 v234, v121, v121
	v_pk_fma_f32 v[122:123], v[122:123], v[138:139], v[236:237]
	v_fmac_f32_e32 v234, v120, v120
	v_add_f32_e32 v233, v233, v234
	v_mul_f32_e32 v234, v123, v123
	v_fmac_f32_e32 v234, v122, v122
	v_pk_fma_f32 v[118:119], v[118:119], v[134:135], v[248:249]
	v_pk_fma_f32 v[116:117], v[116:117], v[132:133], v[246:247]
	v_add_f32_e32 v233, v234, v233
	v_mul_f32_e32 v234, v117, v117
	v_mul_f32_e32 v235, v119, v119
	v_pk_fma_f32 v[112:113], v[112:113], v[128:129], v[242:243]
	v_fmac_f32_e32 v234, v116, v116
	v_fmac_f32_e32 v235, v118, v118
	v_add_f32_e32 v234, v234, v235
	v_mul_f32_e32 v235, v113, v113
	v_pk_fma_f32 v[114:115], v[114:115], v[130:131], v[244:245]
	v_fmac_f32_e32 v235, v112, v112
	v_add_f32_e32 v234, v234, v235
	v_mul_f32_e32 v235, v115, v115
	v_fmac_f32_e32 v235, v114, v114
	v_add_f32_e32 v234, v235, v234
	v_add_f32_e32 v233, v233, v234
	ds_bpermute_b32 v234, v209, v233
	s_waitcnt lgkmcnt(0)
	v_add_f32_e32 v233, v233, v234
	ds_bpermute_b32 v234, v211, v233
	s_and_saveexec_b64 s[44:45], vcc
	s_cbranch_execz .LBB0_510
	v_lshlrev_b64 v[236:237], 6, v[216:217]
	v_lshl_add_u64 v[236:237], s[12:13], 0, v[236:237]
	v_lshl_add_u64 v[236:237], s[42:43], 2, v[236:237]
	s_lshl_b32 s8, s71, 2
	v_lshl_add_u64 v[236:237], v[236:237], 0, s[8:9]
	s_waitcnt lgkmcnt(0)
	v_add_f32_e32 v217, v233, v234
	global_store_dword v[236:237], v217, off

.LBB0_516:
	s_or_b64 exec, exec, s[44:45]
	v_add_u32_e32 v224, 0x80, v216
	v_ashrrev_i32_e32 v225, 31, v224
	s_waitcnt lgkmcnt(0)
	v_lshlrev_b64 v[64:65], 12, v[224:225]
	v_add_u32_e32 v222, 0x90, v216
	v_lshl_add_u64 v[64:65], v[218:219], 0, v[64:65]
	v_ashrrev_i32_e32 v223, 31, v222
	global_load_dwordx4 v[234:237], v[64:65], off offset:16 nt
	global_load_dwordx4 v[238:241], v[64:65], off nt
	global_load_dwordx4 v[242:245], v[64:65], off offset:528 nt
	global_load_dwordx4 v[246:249], v[64:65], off offset:512 nt
	v_lshlrev_b64 v[64:65], 12, v[222:223]
	v_add_u32_e32 v220, 0xa0, v216
	v_lshl_add_u64 v[64:65], v[218:219], 0, v[64:65]
	v_ashrrev_i32_e32 v221, 31, v220
	global_load_dwordx4 v[104:107], v[64:65], off offset:16 nt
	global_load_dwordx4 v[108:111], v[64:65], off nt
	global_load_dwordx4 v[96:99], v[64:65], off offset:528 nt
	global_load_dwordx4 v[100:103], v[64:65], off offset:512 nt
	v_lshlrev_b64 v[64:65], 12, v[220:221]
	v_add_u32_e32 v216, 0xb0, v216
	v_lshl_add_u64 v[64:65], v[218:219], 0, v[64:65]
	v_ashrrev_i32_e32 v217, 31, v216
	global_load_dwordx4 v[88:91], v[64:65], off offset:16 nt
	global_load_dwordx4 v[92:95], v[64:65], off nt
	global_load_dwordx4 v[80:83], v[64:65], off offset:528 nt
	global_load_dwordx4 v[84:87], v[64:65], off offset:512 nt
	v_lshlrev_b64 v[64:65], 12, v[216:217]
	v_lshl_add_u64 v[68:69], v[218:219], 0, v[64:65]
	global_load_dwordx4 v[72:75], v[68:69], off offset:16 nt
	global_load_dwordx4 v[76:79], v[68:69], off nt
	global_load_dwordx4 v[64:67], v[68:69], off offset:528 nt
	s_nop 0
	global_load_dwordx4 v[68:71], v[68:69], off offset:512 nt
	s_waitcnt vmcnt(14)
	v_pk_fma_f32 v[62:63], v[62:63], v[142:143], v[240:241]
	v_pk_fma_f32 v[60:61], v[60:61], v[140:141], v[238:239]
	v_mul_f32_e32 v219, v63, v63
	v_mul_f32_e32 v218, v61, v61
	v_pk_fma_f32 v[56:57], v[56:57], v[136:137], v[234:235]
	v_fmac_f32_e32 v218, v60, v60
	v_fmac_f32_e32 v219, v62, v62
	v_add_f32_e32 v218, v218, v219
	v_mul_f32_e32 v219, v57, v57
	v_pk_fma_f32 v[58:59], v[58:59], v[138:139], v[236:237]
	v_fmac_f32_e32 v219, v56, v56
	v_add_f32_e32 v218, v218, v219
	v_mul_f32_e32 v219, v59, v59
	v_fmac_f32_e32 v219, v58, v58
	s_waitcnt vmcnt(12)
	v_pk_fma_f32 v[54:55], v[54:55], v[134:135], v[248:249]
	v_pk_fma_f32 v[52:53], v[52:53], v[132:133], v[246:247]
	v_add_f32_e32 v218, v219, v218
	v_mul_f32_e32 v219, v53, v53
	v_mul_f32_e32 v233, v55, v55
	v_pk_fma_f32 v[48:49], v[48:49], v[128:129], v[242:243]
	v_fmac_f32_e32 v219, v52, v52
	v_fmac_f32_e32 v233, v54, v54
	v_add_f32_e32 v219, v219, v233
	v_mul_f32_e32 v233, v49, v49
	v_pk_fma_f32 v[50:51], v[50:51], v[130:131], v[244:245]
	v_fmac_f32_e32 v233, v48, v48
	v_add_f32_e32 v219, v219, v233
	v_mul_f32_e32 v233, v51, v51
	v_fmac_f32_e32 v233, v50, v50
	v_add_f32_e32 v219, v233, v219
	v_add_f32_e32 v218, v218, v219
	ds_bpermute_b32 v219, v209, v218
	s_waitcnt lgkmcnt(0)
	v_add_f32_e32 v218, v218, v219
	ds_bpermute_b32 v219, v211, v218
	s_and_saveexec_b64 s[44:45], vcc
	s_cbranch_execz .LBB0_518
	v_lshlrev_b64 v[224:225], 6, v[224:225]
	v_lshl_add_u64 v[224:225], s[12:13], 0, v[224:225]
	v_lshl_add_u64 v[224:225], s[42:43], 2, v[224:225]
	s_lshl_b32 s8, s71, 2
	v_lshl_add_u64 v[224:225], v[224:225], 0, s[8:9]
	s_waitcnt lgkmcnt(0)
	v_add_f32_e32 v218, v218, v219
	global_store_dword v[224:225], v218, off
